# v47 plus scalar path trims at the tile edge: 32-bit tile index, folded first-iteration pointer selects, single-branch tile back-edge
# speedup vs baseline: 1.0078x; 1.0043x over previous
;     __device__ bool next(int i, Unit& u) const {
;         int t = i, b = 0; if (nb == 3) { t = i / 3; b = i - 3 * t; }
;         const long L = (long)t * G + c; if (L >= nwg) return false;
;         int wgid = (int)L; { const int q = nwg / NXCD, r = nwg % NXCD, xcd = wgid % NXCD, off = wgid / NXCD; wgid = (xcd < r ? xcd * (q + 1) : r * (q + 1) + (xcd - r) * q) + off; }
;         const int nig = WGM * nN, gid = wgid / nig, fm = gid * WGM, gsz = (nM - fm) < WGM ? (nM - fm) : WGM;
;         u.pm = fm + ((wgid % nig) % gsz); u.pn = (wgid % nig) / gsz; u.b = b; return true;
; template <class Epi, class Sched>
; __device__ __forceinline__ void gemm_phase(LAS unsigned char* lds, const Gemm g, const Sched& S, const Epi& E) {
;     ...
;         const bool has_next = S.next(ui + 1, nxt);
.LBB0_277:
	s_add_i32 s58, s58, 1
	s_mul_i32 s14, s58, s96
	s_add_u32 s14, s14, s29
	s_cmp_lt_u32 s14, 0x1800
	s_cselect_b64 s[40:41], -1, 0
	s_cbranch_scc0 .LBB0_279
	s_lshr_b32 s15, s14, 3
	s_and_b32 s6, s14, 7
	s_mulk_i32 s6, 0x300
	s_add_i32 s6, s6, s15
	s_mul_hi_u32 s14, s6, 0x2aaaaaab
	s_lshr_b32 s14, s14, 5
	s_lshl_b32 s15, s14, 2
	s_mulk_i32 s14, 0xc0
	s_sub_i32 s6, s6, s14
	s_lshr_b32 s16, s6, 2
	s_and_b32 s6, s6, 3
	s_add_i32 s18, s15, s6

; #define PG8_STAGE(bufoff, gbase, voff) do { _Pragma("unroll") for (int _i = 0; _i < 2; ++_i) \
;         __builtin_amdgcn_global_load_lds((const unsigned*)((const char*)(gbase) + (voff)[_i]), (LAS unsigned*)(lds + (bufoff) + ldsw + _i * 8192), 16, 0, 0); } while (0)
; #define PG8_LDA(dst, b, h) do { _Pragma("unroll") for (int m = 0; m < 4; ++m) _Pragma("unroll") for (int k = 0; k < 2; ++k) dst[m][k] = *(const LAS bf16x8*)(lds + PG8_SA(b, h) + aoff + m * 2048 + k * 1024); } while (0)
; #define PG8_LDB(dst, b, h) do { _Pragma("unroll") for (int n = 0; n < 2; ++n) _Pragma("unroll") for (int k = 0; k < 2; ++k) dst[n][k] = *(const LAS bf16x8*)(lds + PG8_SB(b, h) + boff + n * 2048 + k * 1024); } while (0)
; #define PG8_MMA(ai, bj, At, Bt) do { __builtin_amdgcn_s_setprio(1); _Pragma("unroll") for (int m = 0; m < 4; ++m) _Pragma("unroll") for (int n = 0; n < 2; ++n) _Pragma("unroll") for (int k = 0; k < 2; ++k) \
;         acc[ai][bj][m][n] = __builtin_amdgcn_mfma_f32_16x16x32_bf16(Bt[n][k], At[m][k], acc[ai][bj][m][n], 0, 0, 0); __builtin_amdgcn_s_setprio(0); } while (0)
; #define PG8_WAIT_V(n) asm volatile("s_waitcnt vmcnt(" #n ")" ::: "memory")
; #define PG8_WAIT_L(n) asm volatile("s_waitcnt lgkmcnt(" #n ")" ::: "memory")
; #define PG8_BAR __builtin_amdgcn_s_barrier()
; #define PG8_SCHED __builtin_amdgcn_sched_barrier(0)
; template <class Epi, class Sched>
; __device__ __forceinline__ void gemm_phase(LAS unsigned char* lds, const Gemm g, const Sched& S, const Epi& E) {
;     ...
;             PG8_LDB(B0, 0, 0); PG8_LDB(B1, 0, 1); PG8_SCHED; PG8_LDA(At, 0, 0); PG8_STAGE(PG8_SA(1, 1), a1 + hstepA, voffA);
;             PG8_WAIT_V(8); PG8_WAIT_L(0); PG8_BAR; PG8_MMA(0, 0, At, B0); PG8_MMA(0, 1, At, B1); PG8_BAR; PG8_SCHED;
;             PG8_LDA(At, 0, 1); PG8_STAGE(PG8_SB(0, 0), b2, voffB); PG8_STAGE(PG8_SB(0, 1), b2 + hstepB, voffB); PG8_STAGE(PG8_SA(0, 0), a2, voffA);
;             PG8_WAIT_V(8); PG8_WAIT_L(0); PG8_BAR; PG8_MMA(1, 0, At, B0); PG8_MMA(1, 1, At, B1); PG8_BAR; PG8_SCHED;
.Lp1_nobar:
	s_add_u32 s36, s24, 0xfffc0080
	s_addc_u32 s37, s25, -1
	s_mov_b32 s44, 0x10000
	v_add_u32_e32 v145, s44, v165
	s_mov_b32 s27, s42
	s_mov_b32 s26, s19
	s_mov_b32 s46, 0x14000
	ds_read_b128 v[148:151], v145
	ds_read_b128 v[152:155], v145 offset:1024
	ds_read_b128 v[156:159], v145 offset:2048
	ds_read_b128 v[160:163], v145 offset:3072
	v_add_u32_e32 v145, s46, v165
	ds_read_b128 v[168:171], v145
	ds_read_b128 v[172:175], v145 offset:1024
	ds_read_b128 v[176:179], v145 offset:2048
	ds_read_b128 v[180:183], v145 offset:3072
	s_add_i32 m0, s52, 0xc000
	ds_read_b128 v[184:187], v167
	ds_read_b128 v[188:191], v167 offset:1024
	ds_read_b128 v[192:195], v167 offset:2048
	ds_read_b128 v[196:199], v167 offset:3072
	ds_read_b128 v[200:203], v167 offset:4096
	ds_read_b128 v[204:207], v167 offset:5120
	ds_read_b128 v[208:211], v167 offset:6144
	ds_read_b128 v[214:217], v167 offset:7168
	global_load_lds_dwordx4 v140, s[24:25]
	s_add_i32 m0, s52, 0xe000
	s_nop 0
	global_load_lds_dwordx4 v142, s[24:25]
	s_waitcnt vmcnt(8)
	s_waitcnt lgkmcnt(0)
	s_barrier
	s_setprio 1
	s_waitcnt lgkmcnt(0)
	v_mfma_f32_16x16x32_bf16 v[124:127], v[148:151], v[184:187], 0
	v_mfma_f32_16x16x32_bf16 v[120:123], v[156:159], v[184:187], 0
	v_mfma_f32_16x16x32_bf16 v[108:111], v[148:151], v[192:195], 0
	v_mfma_f32_16x16x32_bf16 v[104:107], v[156:159], v[192:195], 0
	v_mfma_f32_16x16x32_bf16 v[92:95], v[148:151], v[200:203], 0
	v_mfma_f32_16x16x32_bf16 v[88:91], v[156:159], v[200:203], 0
	v_mfma_f32_16x16x32_bf16 v[76:79], v[148:151], v[208:211], 0
	v_mfma_f32_16x16x32_bf16 v[72:75], v[156:159], v[208:211], 0
	v_mfma_f32_16x16x32_bf16 v[124:127], v[152:155], v[188:191], v[124:127]
	v_mfma_f32_16x16x32_bf16 v[120:123], v[160:163], v[188:191], v[120:123]
	v_mfma_f32_16x16x32_bf16 v[108:111], v[152:155], v[196:199], v[108:111]
	v_mfma_f32_16x16x32_bf16 v[104:107], v[160:163], v[196:199], v[104:107]
	v_mfma_f32_16x16x32_bf16 v[92:95], v[152:155], v[204:207], v[92:95]
	v_mfma_f32_16x16x32_bf16 v[88:91], v[160:163], v[204:207], v[88:91]
	v_mfma_f32_16x16x32_bf16 v[76:79], v[152:155], v[214:217], v[76:79]
	v_mfma_f32_16x16x32_bf16 v[72:75], v[160:163], v[214:217], v[72:75]
	s_setprio 0
	s_setprio 1
	v_mfma_f32_16x16x32_bf16 v[116:119], v[168:171], v[184:187], 0
	v_mfma_f32_16x16x32_bf16 v[112:115], v[176:179], v[184:187], 0
	v_mfma_f32_16x16x32_bf16 v[100:103], v[168:171], v[192:195], 0
	v_mfma_f32_16x16x32_bf16 v[96:99], v[176:179], v[192:195], 0
	v_mfma_f32_16x16x32_bf16 v[84:87], v[168:171], v[200:203], 0
	v_mfma_f32_16x16x32_bf16 v[80:83], v[176:179], v[200:203], 0
	v_mfma_f32_16x16x32_bf16 v[68:71], v[168:171], v[208:211], 0
	v_mfma_f32_16x16x32_bf16 v[64:67], v[176:179], v[208:211], 0
	v_mfma_f32_16x16x32_bf16 v[116:119], v[172:175], v[188:191], v[116:119]
	v_mfma_f32_16x16x32_bf16 v[112:115], v[180:183], v[188:191], v[112:115]
	v_mfma_f32_16x16x32_bf16 v[100:103], v[172:175], v[196:199], v[100:103]
	v_mfma_f32_16x16x32_bf16 v[96:99], v[180:183], v[196:199], v[96:99]
	v_mfma_f32_16x16x32_bf16 v[84:87], v[172:175], v[204:207], v[84:87]
	v_mfma_f32_16x16x32_bf16 v[80:83], v[180:183], v[204:207], v[80:83]
	v_mfma_f32_16x16x32_bf16 v[68:71], v[172:175], v[214:217], v[68:71]
	v_mfma_f32_16x16x32_bf16 v[64:67], v[180:183], v[214:217], v[64:67]
	s_setprio 0
	s_barrier
	s_add_i32 s44, s44, s2
	s_mov_b32 m0, s44
	ds_read_b128 v[184:187], v167 offset:16384
	ds_read_b128 v[188:191], v167 offset:17408
	ds_read_b128 v[192:195], v167 offset:18432
	ds_read_b128 v[196:199], v167 offset:19456
	ds_read_b128 v[200:203], v167 offset:20480
	ds_read_b128 v[204:207], v167 offset:21504
	ds_read_b128 v[208:211], v167 offset:22528
	ds_read_b128 v[214:217], v167 offset:23552
	global_load_lds_dwordx4 v132, s[26:27]
	s_add_i32 m0, s44, 0x2000
	s_add_u32 s44, s26, 0x40000
	s_addc_u32 s45, s27, 0
	s_add_i32 s46, s46, s2
	global_load_lds_dwordx4 v128, s[26:27]
	s_mov_b32 m0, s46
	s_nop 0
	global_load_lds_dwordx4 v132, s[44:45]
	s_add_i32 m0, s46, 0x2000
	s_nop 0
	global_load_lds_dwordx4 v128, s[44:45]
	s_mov_b32 m0, s52
	s_nop 0
	global_load_lds_dwordx4 v134, s[36:37]
	s_mov_b32 m0, s53
	s_nop 0
	global_load_lds_dwordx4 v130, s[36:37]
	s_waitcnt vmcnt(8)
	s_waitcnt lgkmcnt(0)
	s_barrier
	s_setprio 1
	s_waitcnt lgkmcnt(0)
	v_mfma_f32_16x16x32_bf16 v[60:63], v[148:151], v[184:187], 0
	v_mfma_f32_16x16x32_bf16 v[56:59], v[156:159], v[184:187], 0
	v_mfma_f32_16x16x32_bf16 v[44:47], v[148:151], v[192:195], 0
	v_mfma_f32_16x16x32_bf16 v[40:43], v[156:159], v[192:195], 0
	v_mfma_f32_16x16x32_bf16 v[28:31], v[148:151], v[200:203], 0
	v_mfma_f32_16x16x32_bf16 v[24:27], v[156:159], v[200:203], 0
	v_mfma_f32_16x16x32_bf16 v[12:15], v[148:151], v[208:211], 0
	v_mfma_f32_16x16x32_bf16 v[8:11], v[156:159], v[208:211], 0
	v_mfma_f32_16x16x32_bf16 v[60:63], v[152:155], v[188:191], v[60:63]
	v_mfma_f32_16x16x32_bf16 v[56:59], v[160:163], v[188:191], v[56:59]
	v_mfma_f32_16x16x32_bf16 v[44:47], v[152:155], v[196:199], v[44:47]
	v_mfma_f32_16x16x32_bf16 v[40:43], v[160:163], v[196:199], v[40:43]
	v_mfma_f32_16x16x32_bf16 v[28:31], v[152:155], v[204:207], v[28:31]
	v_mfma_f32_16x16x32_bf16 v[24:27], v[160:163], v[204:207], v[24:27]
	v_mfma_f32_16x16x32_bf16 v[12:15], v[152:155], v[214:217], v[12:15]
	v_mfma_f32_16x16x32_bf16 v[8:11], v[160:163], v[214:217], v[8:11]
	s_setprio 0
	s_setprio 1
	v_mfma_f32_16x16x32_bf16 v[52:55], v[168:171], v[184:187], 0
	v_mfma_f32_16x16x32_bf16 v[48:51], v[176:179], v[184:187], 0
	v_mfma_f32_16x16x32_bf16 v[36:39], v[168:171], v[192:195], 0
	v_mfma_f32_16x16x32_bf16 v[32:35], v[176:179], v[192:195], 0
	v_mfma_f32_16x16x32_bf16 v[20:23], v[168:171], v[200:203], 0
	v_mfma_f32_16x16x32_bf16 v[16:19], v[176:179], v[200:203], 0
	v_mfma_f32_16x16x32_bf16 v[4:7], v[168:171], v[208:211], 0
	v_mfma_f32_16x16x32_bf16 v[0:3], v[176:179], v[208:211], 0
	v_mfma_f32_16x16x32_bf16 v[52:55], v[172:175], v[188:191], v[52:55]
	v_mfma_f32_16x16x32_bf16 v[48:51], v[180:183], v[188:191], v[48:51]
	v_mfma_f32_16x16x32_bf16 v[36:39], v[172:175], v[196:199], v[36:39]
	v_mfma_f32_16x16x32_bf16 v[32:35], v[180:183], v[196:199], v[32:35]
	v_mfma_f32_16x16x32_bf16 v[20:23], v[172:175], v[204:207], v[20:23]
	v_mfma_f32_16x16x32_bf16 v[16:19], v[180:183], v[204:207], v[16:19]
	v_mfma_f32_16x16x32_bf16 v[4:7], v[172:175], v[214:217], v[4:7]
	v_mfma_f32_16x16x32_bf16 v[0:3], v[180:183], v[214:217], v[0:3]
	s_setprio 0
	s_barrier
; #define PG8_STAGE(bufoff, gbase, voff) do { _Pragma("unroll") for (int _i = 0; _i < 2; ++_i) \
;         __builtin_amdgcn_global_load_lds((const unsigned*)((const char*)(gbase) + (voff)[_i]), (LAS unsigned*)(lds + (bufoff) + ldsw + _i * 8192), 16, 0, 0); } while (0)
; #define PG8_LDA(dst, b, h) do { _Pragma("unroll") for (int m = 0; m < 4; ++m) _Pragma("unroll") for (int k = 0; k < 2; ++k) dst[m][k] = *(const LAS bf16x8*)(lds + PG8_SA(b, h) + aoff + m * 2048 + k * 1024); } while (0)
; #define PG8_LDB(dst, b, h) do { _Pragma("unroll") for (int n = 0; n < 2; ++n) _Pragma("unroll") for (int k = 0; k < 2; ++k) dst[n][k] = *(const LAS bf16x8*)(lds + PG8_SB(b, h) + boff + n * 2048 + k * 1024); } while (0)
; #define PG8_MMA(ai, bj, At, Bt) do { __builtin_amdgcn_s_setprio(1); _Pragma("unroll") for (int m = 0; m < 4; ++m) _Pragma("unroll") for (int n = 0; n < 2; ++n) _Pragma("unroll") for (int k = 0; k < 2; ++k) \
;         acc[ai][bj][m][n] = __builtin_amdgcn_mfma_f32_16x16x32_bf16(Bt[n][k], At[m][k], acc[ai][bj][m][n], 0, 0, 0); __builtin_amdgcn_s_setprio(0); } while (0)
; #define PG8_WAIT_V(n) asm volatile("s_waitcnt vmcnt(" #n ")" ::: "memory")
; #define PG8_WAIT_L(n) asm volatile("s_waitcnt lgkmcnt(" #n ")" ::: "memory")
; #define PG8_BAR __builtin_amdgcn_s_barrier()
; #define PG8_SCHED __builtin_amdgcn_sched_barrier(0)
; template <class Epi, class Sched>
; __device__ __forceinline__ void gemm_phase(LAS unsigned char* lds, const Gemm g, const Sched& S, const Epi& E) {
;     ...
;             PG8_LDB(B0, 1, 0); PG8_LDB(B1, 1, 1); PG8_SCHED; PG8_LDA(At, 1, 0); PG8_STAGE(PG8_SA(0, 1), a2 + hstepA, voffA);
;             PG8_WAIT_V(8); PG8_WAIT_L(0); PG8_BAR; PG8_MMA(0, 0, At, B0); PG8_MMA(0, 1, At, B1); PG8_BAR; PG8_SCHED;
;             PG8_LDA(At, 1, 1); PG8_STAGE(PG8_SB(1, 0), b3, voffB); PG8_STAGE(PG8_SB(1, 1), b3 + hstepB, voffB); PG8_STAGE(PG8_SA(1, 0), a3, voffA);
;             PG8_WAIT_V(8); PG8_WAIT_L(0); PG8_BAR; PG8_MMA(1, 0, At, B0); PG8_MMA(1, 1, At, B1); PG8_BAR; PG8_SCHED;
	s_add_i32 s44, 0, 0x18000
	v_add_u32_e32 v145, s44, v165
	s_add_i32 s45, 0, 0x1c000
	ds_read_b128 v[148:151], v145
	ds_read_b128 v[152:155], v145 offset:1024
	ds_read_b128 v[156:159], v145 offset:2048
	ds_read_b128 v[160:163], v145 offset:3072
	v_add_u32_e32 v145, s45, v165
	ds_read_b128 v[168:171], v145
	ds_read_b128 v[172:175], v145 offset:1024
	ds_read_b128 v[176:179], v145 offset:2048
	ds_read_b128 v[180:183], v145 offset:3072
	s_add_u32 s36, s36, 0x40000
	s_addc_u32 s37, s37, 0
	s_mov_b32 m0, s54
	ds_read_b128 v[184:187], v167 offset:32768
	ds_read_b128 v[188:191], v167 offset:33792
	ds_read_b128 v[192:195], v167 offset:34816
	ds_read_b128 v[196:199], v167 offset:35840
	ds_read_b128 v[200:203], v167 offset:36864
	ds_read_b128 v[204:207], v167 offset:37888
	ds_read_b128 v[208:211], v167 offset:38912
	ds_read_b128 v[214:217], v167 offset:39936
	global_load_lds_dwordx4 v134, s[36:37]
	s_mov_b32 m0, s55
	s_nop 0
	global_load_lds_dwordx4 v130, s[36:37]
	s_waitcnt vmcnt(8)
	s_waitcnt lgkmcnt(0)
	s_barrier
	s_setprio 1
	s_waitcnt lgkmcnt(0)
	v_mfma_f32_16x16x32_bf16 v[124:127], v[148:151], v[184:187], v[124:127]
	v_mfma_f32_16x16x32_bf16 v[120:123], v[156:159], v[184:187], v[120:123]
	v_mfma_f32_16x16x32_bf16 v[108:111], v[148:151], v[192:195], v[108:111]
	v_mfma_f32_16x16x32_bf16 v[104:107], v[156:159], v[192:195], v[104:107]
	v_mfma_f32_16x16x32_bf16 v[92:95], v[148:151], v[200:203], v[92:95]
	v_mfma_f32_16x16x32_bf16 v[88:91], v[156:159], v[200:203], v[88:91]
	v_mfma_f32_16x16x32_bf16 v[76:79], v[148:151], v[208:211], v[76:79]
	v_mfma_f32_16x16x32_bf16 v[72:75], v[156:159], v[208:211], v[72:75]
	v_mfma_f32_16x16x32_bf16 v[124:127], v[152:155], v[188:191], v[124:127]
	v_mfma_f32_16x16x32_bf16 v[120:123], v[160:163], v[188:191], v[120:123]
	v_mfma_f32_16x16x32_bf16 v[108:111], v[152:155], v[196:199], v[108:111]
	v_mfma_f32_16x16x32_bf16 v[104:107], v[160:163], v[196:199], v[104:107]
	v_mfma_f32_16x16x32_bf16 v[92:95], v[152:155], v[204:207], v[92:95]
	v_mfma_f32_16x16x32_bf16 v[88:91], v[160:163], v[204:207], v[88:91]
	v_mfma_f32_16x16x32_bf16 v[76:79], v[152:155], v[214:217], v[76:79]
	v_mfma_f32_16x16x32_bf16 v[72:75], v[160:163], v[214:217], v[72:75]
	s_setprio 0
	s_setprio 1
	v_mfma_f32_16x16x32_bf16 v[116:119], v[168:171], v[184:187], v[116:119]
	v_mfma_f32_16x16x32_bf16 v[112:115], v[176:179], v[184:187], v[112:115]
	v_mfma_f32_16x16x32_bf16 v[100:103], v[168:171], v[192:195], v[100:103]
	v_mfma_f32_16x16x32_bf16 v[96:99], v[176:179], v[192:195], v[96:99]
	v_mfma_f32_16x16x32_bf16 v[84:87], v[168:171], v[200:203], v[84:87]
	v_mfma_f32_16x16x32_bf16 v[80:83], v[176:179], v[200:203], v[80:83]
	v_mfma_f32_16x16x32_bf16 v[68:71], v[168:171], v[208:211], v[68:71]
	v_mfma_f32_16x16x32_bf16 v[64:67], v[176:179], v[208:211], v[64:67]
	v_mfma_f32_16x16x32_bf16 v[116:119], v[172:175], v[188:191], v[116:119]
	v_mfma_f32_16x16x32_bf16 v[112:115], v[180:183], v[188:191], v[112:115]
	v_mfma_f32_16x16x32_bf16 v[100:103], v[172:175], v[196:199], v[100:103]
	v_mfma_f32_16x16x32_bf16 v[96:99], v[180:183], v[196:199], v[96:99]
	v_mfma_f32_16x16x32_bf16 v[84:87], v[172:175], v[204:207], v[84:87]
	v_mfma_f32_16x16x32_bf16 v[80:83], v[180:183], v[204:207], v[80:83]
	v_mfma_f32_16x16x32_bf16 v[68:71], v[172:175], v[214:217], v[68:71]
	v_mfma_f32_16x16x32_bf16 v[64:67], v[180:183], v[214:217], v[64:67]
	s_setprio 0
	s_barrier
	s_add_u32 s98, s36, 0xfffc0080
	s_addc_u32 s99, s37, -1
	s_add_u32 s62, s26, 0x80
	s_addc_u32 s63, s27, 0
	s_add_i32 s36, s44, s2
	s_mov_b32 m0, s36
	ds_read_b128 v[184:187], v167 offset:49152
	ds_read_b128 v[188:191], v167 offset:50176
	ds_read_b128 v[192:195], v167 offset:51200
	ds_read_b128 v[196:199], v167 offset:52224
	ds_read_b128 v[200:203], v167 offset:53248
	ds_read_b128 v[204:207], v167 offset:54272
	ds_read_b128 v[208:211], v167 offset:55296
	ds_read_b128 v[214:217], v167 offset:56320
	global_load_lds_dwordx4 v132, s[62:63]
	s_add_i32 m0, s36, 0x2000
	s_add_u32 s26, s26, 0x40080
	s_addc_u32 s27, s27, 0
	s_add_i32 s36, s45, s2
	global_load_lds_dwordx4 v128, s[62:63]
	s_mov_b32 m0, s36
	s_nop 0
	global_load_lds_dwordx4 v132, s[26:27]
	s_add_i32 m0, s36, 0x2000
	s_nop 0
	global_load_lds_dwordx4 v128, s[26:27]
	s_mov_b32 m0, s56
	s_nop 0
	global_load_lds_dwordx4 v134, s[98:99]
	s_mov_b32 m0, s57
	s_nop 0
	global_load_lds_dwordx4 v130, s[98:99]
	s_waitcnt vmcnt(8)
	s_waitcnt lgkmcnt(0)
	s_barrier
	s_setprio 1
	s_waitcnt lgkmcnt(0)
	v_mfma_f32_16x16x32_bf16 v[60:63], v[148:151], v[184:187], v[60:63]
	v_mfma_f32_16x16x32_bf16 v[56:59], v[156:159], v[184:187], v[56:59]
	v_mfma_f32_16x16x32_bf16 v[44:47], v[148:151], v[192:195], v[44:47]
	v_mfma_f32_16x16x32_bf16 v[40:43], v[156:159], v[192:195], v[40:43]
	v_mfma_f32_16x16x32_bf16 v[28:31], v[148:151], v[200:203], v[28:31]
	v_mfma_f32_16x16x32_bf16 v[24:27], v[156:159], v[200:203], v[24:27]
	v_mfma_f32_16x16x32_bf16 v[12:15], v[148:151], v[208:211], v[12:15]
	v_mfma_f32_16x16x32_bf16 v[8:11], v[156:159], v[208:211], v[8:11]
	v_mfma_f32_16x16x32_bf16 v[60:63], v[152:155], v[188:191], v[60:63]
	v_mfma_f32_16x16x32_bf16 v[56:59], v[160:163], v[188:191], v[56:59]
	v_mfma_f32_16x16x32_bf16 v[44:47], v[152:155], v[196:199], v[44:47]
	v_mfma_f32_16x16x32_bf16 v[40:43], v[160:163], v[196:199], v[40:43]
	v_mfma_f32_16x16x32_bf16 v[28:31], v[152:155], v[204:207], v[28:31]
	v_mfma_f32_16x16x32_bf16 v[24:27], v[160:163], v[204:207], v[24:27]
	v_mfma_f32_16x16x32_bf16 v[12:15], v[152:155], v[214:217], v[12:15]
	v_mfma_f32_16x16x32_bf16 v[8:11], v[160:163], v[214:217], v[8:11]
	s_setprio 0
	s_setprio 1
	v_mfma_f32_16x16x32_bf16 v[52:55], v[168:171], v[184:187], v[52:55]
	v_mfma_f32_16x16x32_bf16 v[48:51], v[176:179], v[184:187], v[48:51]
	v_mfma_f32_16x16x32_bf16 v[36:39], v[168:171], v[192:195], v[36:39]
	v_mfma_f32_16x16x32_bf16 v[32:35], v[176:179], v[192:195], v[32:35]
	v_mfma_f32_16x16x32_bf16 v[20:23], v[168:171], v[200:203], v[20:23]
	v_mfma_f32_16x16x32_bf16 v[16:19], v[176:179], v[200:203], v[16:19]
	v_mfma_f32_16x16x32_bf16 v[4:7], v[168:171], v[208:211], v[4:7]
	v_mfma_f32_16x16x32_bf16 v[0:3], v[176:179], v[208:211], v[0:3]
	v_mfma_f32_16x16x32_bf16 v[52:55], v[172:175], v[188:191], v[52:55]
	v_mfma_f32_16x16x32_bf16 v[48:51], v[180:183], v[188:191], v[48:51]
	v_mfma_f32_16x16x32_bf16 v[36:39], v[172:175], v[196:199], v[36:39]
	v_mfma_f32_16x16x32_bf16 v[32:35], v[180:183], v[196:199], v[32:35]
	v_mfma_f32_16x16x32_bf16 v[20:23], v[172:175], v[204:207], v[20:23]
	v_mfma_f32_16x16x32_bf16 v[16:19], v[180:183], v[204:207], v[16:19]
	v_mfma_f32_16x16x32_bf16 v[4:7], v[172:175], v[214:217], v[4:7]
	v_mfma_f32_16x16x32_bf16 v[0:3], v[180:183], v[214:217], v[0:3]
	s_setprio 0
	s_barrier
	s_add_i32 s43, s43, 2
	s_add_u32 s24, s24, 0x100
	s_addc_u32 s25, s25, 0
	s_add_u32 s19, s19, 0x100
	s_addc_u32 s42, s42, 0

;     __device__ __forceinline__ void operator()(f32x4 (&acc)[2][2][4][2], const Unit& u, int wr, int wc, int fr, int fq) const {
;     ...
;             const int row0q = u.pm * BM + wr * 64 + fr; const int ch = 64 * (pn - 32) + 16 * wc + 4 * fq;
; #pragma unroll
;             for (int ai = 0; ai < 2; ++ai)
; #pragma unroll
;                 for (int m = 0; m < 4; ++m) {
;                     bf16_t* rowp = O + (size_t)(row0q + ai * HALF + m * 16) * LDP + ch;
;                     float r0v[4], r1v[4], g2v[4], szv[4];
; #pragma unroll
;                     for (int j = 0; j < 4; ++j) {
;                         const float ea = fminf(__builtin_amdgcn_exp2f(-1.4426950409f * acc[ai][0][m][0][j]), 1e30f);
;                         const float eb = fminf(__builtin_amdgcn_exp2f(-1.4426950409f * acc[ai][0][m][1][j]), 1e30f);
;                         const float ec = fminf(__builtin_amdgcn_exp2f(-1.4426950409f * acc[ai][1][m][0][j]), 1e30f);
;                         const float xz = acc[ai][1][m][1][j];
;                         const float ia = __builtin_amdgcn_rcpf(1.0f + ea), ib = __builtin_amdgcn_rcpf(1.0f + eb), ic = __builtin_amdgcn_rcpf(1.0f + ec);
;                         r0v[j] = (1.0f + eb) * ia; r1v[j] = (1.0f + ec) * ib; g2v[j] = ic; szv[j] = xz * sigmoid_f(xz);
;                     }
;                     u32x2 wr0, wr1, wg2, wsz;
;                     wr0.x = cvt_pk_bf16(r0v[0], r0v[1]); wr0.y = cvt_pk_bf16(r0v[2], r0v[3]);
;                     wr1.x = cvt_pk_bf16(r1v[0], r1v[1]); wr1.y = cvt_pk_bf16(r1v[2], r1v[3]);
;                     wg2.x = cvt_pk_bf16(g2v[0], g2v[1]); wg2.y = cvt_pk_bf16(g2v[2], g2v[3]);
;                     wsz.x = cvt_pk_bf16(szv[0], szv[1]); wsz.y = cvt_pk_bf16(szv[2], szv[3]);
;                     const bool odd = (fq & 1) != 0;
;                     const u32x2 s0 = odd ? wr0 : wg2, s1 = odd ? wr1 : wsz;
;                     u32x2 q0, q1;
;                     q0.x = (unsigned)__shfl_xor((int)s0.x, 16); q0.y = (unsigned)__shfl_xor((int)s0.y, 16);
;                     q1.x = (unsigned)__shfl_xor((int)s1.x, 16); q1.y = (unsigned)__shfl_xor((int)s1.y, 16);
;                     u32x4 o0, o1;
;                     if (!odd) { o0 = (u32x4){wr0.x, wr0.y, q0.x, q0.y}; o1 = (u32x4){wr1.x, wr1.y, q1.x, q1.y}; }
;                     else      { o0 = (u32x4){q0.x, q0.y, wg2.x, wg2.y}; o1 = (u32x4){q1.x, q1.y, wsz.x, wsz.y}; }
.LBB0_298:
	s_mov_b32 s59, s16
	s_mov_b32 s60, s18
	s_mov_b64 s[26:27], s[22:23]
	s_mov_b64 s[24:25], s[20:21]
	s_cmp_eq_u64 s[40:41], 0
	s_cbranch_scc1 .LBB0_492
	s_cmp_eq_u64 s[0:1], 0
	s_cselect_b32 s61, s61, 1
	s_branch .LBB0_277
.LBB0_424:
	v_mov_b32_e32 v184, 8
	v_cndmask_b32_e64 v184, v184, 0, s[38:39]
	v_lshlrev_b32_e32 v185, 11, v164
	v_add_u32_e32 v185, v185, v136
	v_sub_u32_e32 v185, v185, v184
	v_mov_b32_e32 v186, 0x20000000
	v_mov_b32_e32 v187, 0x14000000
	v_cndmask_b32_e64 v186, v186, v187, s[38:39]
	v_add_u32_e32 v150, v185, v186
	v_mov_b32_e32 v186, 0xc000000
	v_mov_b32_e32 v187, 0x1c000000
	v_cndmask_b32_e64 v186, v186, v187, s[38:39]
	v_add_u32_e32 v151, v185, v186
	s_lshl_b32 s14, s60, 19
	s_add_u32 s24, s70, s14
	s_addc_u32 s25, s71, 0
	s_lshl_b32 s14, s59, 7
	s_sub_u32 s14, s14, 0x1000
	s_add_u32 s24, s24, s14
	s_addc_u32 s25, s25, 0
	v_mul_f32_e32 v124, 0xbfb8aa3b, v124
	v_mul_f32_e32 v125, 0xbfb8aa3b, v125
	v_mul_f32_e32 v126, 0xbfb8aa3b, v126
	v_mul_f32_e32 v127, 0xbfb8aa3b, v127
	v_mul_f32_e32 v120, 0xbfb8aa3b, v120
	v_mul_f32_e32 v121, 0xbfb8aa3b, v121
	v_mul_f32_e32 v122, 0xbfb8aa3b, v122
	v_mul_f32_e32 v123, 0xbfb8aa3b, v123
	v_mul_f32_e32 v116, 0xbfb8aa3b, v116
	v_mul_f32_e32 v117, 0xbfb8aa3b, v117
	v_mul_f32_e32 v118, 0xbfb8aa3b, v118
	v_mul_f32_e32 v119, 0xbfb8aa3b, v119
	v_mul_f32_e32 v160, 0xbfb8aa3b, v112
	v_mul_f32_e32 v161, 0xbfb8aa3b, v113
	v_mul_f32_e32 v162, 0xbfb8aa3b, v114
	v_mul_f32_e32 v163, 0xbfb8aa3b, v115
	v_exp_f32_e32 v124, v124
	v_exp_f32_e32 v125, v125
	v_exp_f32_e32 v126, v126
	v_exp_f32_e32 v127, v127
	v_exp_f32_e32 v120, v120
	v_exp_f32_e32 v121, v121
	v_exp_f32_e32 v122, v122
	v_exp_f32_e32 v123, v123
	v_exp_f32_e32 v116, v116
	v_exp_f32_e32 v117, v117
	v_exp_f32_e32 v118, v118
	v_exp_f32_e32 v119, v119
	v_exp_f32_e32 v160, v160
	v_exp_f32_e32 v161, v161
	v_exp_f32_e32 v162, v162
	v_exp_f32_e32 v163, v163
	v_min_f32_e32 v124, 0x7149f2ca, v124
	v_min_f32_e32 v125, 0x7149f2ca, v125
	v_min_f32_e32 v126, 0x7149f2ca, v126
	v_min_f32_e32 v127, 0x7149f2ca, v127
	v_min_f32_e32 v120, 0x7149f2ca, v120
	v_min_f32_e32 v121, 0x7149f2ca, v121
	v_min_f32_e32 v122, 0x7149f2ca, v122
	v_min_f32_e32 v123, 0x7149f2ca, v123
	v_min_f32_e32 v116, 0x7149f2ca, v116
	v_min_f32_e32 v117, 0x7149f2ca, v117
	v_min_f32_e32 v118, 0x7149f2ca, v118
	v_min_f32_e32 v119, 0x7149f2ca, v119
	v_add_f32_e32 v124, 1.0, v124
	v_add_f32_e32 v125, 1.0, v125
	v_add_f32_e32 v126, 1.0, v126
	v_add_f32_e32 v127, 1.0, v127
	v_add_f32_e32 v120, 1.0, v120
	v_add_f32_e32 v121, 1.0, v121
	v_add_f32_e32 v122, 1.0, v122
	v_add_f32_e32 v123, 1.0, v123
	v_add_f32_e32 v116, 1.0, v116
	v_add_f32_e32 v117, 1.0, v117
	v_add_f32_e32 v118, 1.0, v118
	v_add_f32_e32 v119, 1.0, v119
	v_add_f32_e32 v160, 1.0, v160
	v_add_f32_e32 v161, 1.0, v161
	v_add_f32_e32 v162, 1.0, v162
	v_add_f32_e32 v163, 1.0, v163
	v_rcp_f32_e32 v152, v124
	v_rcp_f32_e32 v153, v125
	v_rcp_f32_e32 v154, v126
	v_rcp_f32_e32 v155, v127
	v_rcp_f32_e32 v156, v120
	v_rcp_f32_e32 v157, v121
	v_rcp_f32_e32 v158, v122
	v_rcp_f32_e32 v159, v123
	v_rcp_f32_e32 v160, v160
	v_rcp_f32_e32 v161, v161
	v_rcp_f32_e32 v162, v162
	v_rcp_f32_e32 v163, v163
	v_mul_f32_e32 v152, v120, v152
	v_mul_f32_e32 v153, v121, v153
	v_mul_f32_e32 v154, v122, v154
	v_mul_f32_e32 v155, v123, v155
	v_mul_f32_e32 v156, v116, v156
	v_mul_f32_e32 v157, v117, v157
	v_mul_f32_e32 v158, v118, v158
	v_mul_f32_e32 v159, v119, v159
	v_rcp_f32_e32 v116, v116
	v_rcp_f32_e32 v117, v117
	v_rcp_f32_e32 v118, v118
	v_rcp_f32_e32 v119, v119
	v_mul_f32_e32 v160, v112, v160
	v_mul_f32_e32 v161, v113, v161
	v_mul_f32_e32 v162, v114, v162
	v_mul_f32_e32 v163, v115, v163
	v_cvt_pk_bf16_f32 v168, v152, v153
	v_cvt_pk_bf16_f32 v169, v154, v155
	v_cvt_pk_bf16_f32 v172, v156, v157
	v_cvt_pk_bf16_f32 v173, v158, v159
	v_cvt_pk_bf16_f32 v174, v160, v161
	v_cvt_pk_bf16_f32 v175, v162, v163
	v_cvt_pk_bf16_f32 v170, v116, v117
	v_cvt_pk_bf16_f32 v171, v118, v119
	s_nop 1
	v_permlane16_swap_b32_e32 v172, v174
	v_permlane16_swap_b32_e32 v173, v175
	v_permlane16_swap_b32_e32 v168, v170
	v_permlane16_swap_b32_e32 v169, v171
	global_store_dwordx4 v151, v[172:175], s[24:25]
	global_store_dwordx4 v150, v[168:171], s[24:25]
	s_add_u32 s24, s24, 0x8000
	s_addc_u32 s25, s25, 0
	v_mul_f32_e32 v108, 0xbfb8aa3b, v108
	v_mul_f32_e32 v109, 0xbfb8aa3b, v109
	v_mul_f32_e32 v110, 0xbfb8aa3b, v110
	v_mul_f32_e32 v111, 0xbfb8aa3b, v111
	v_mul_f32_e32 v104, 0xbfb8aa3b, v104
	v_mul_f32_e32 v105, 0xbfb8aa3b, v105
	v_mul_f32_e32 v106, 0xbfb8aa3b, v106
	v_mul_f32_e32 v107, 0xbfb8aa3b, v107
	v_mul_f32_e32 v100, 0xbfb8aa3b, v100
	v_mul_f32_e32 v101, 0xbfb8aa3b, v101
	v_mul_f32_e32 v102, 0xbfb8aa3b, v102
	v_mul_f32_e32 v103, 0xbfb8aa3b, v103
	v_mul_f32_e32 v160, 0xbfb8aa3b, v96
	v_mul_f32_e32 v161, 0xbfb8aa3b, v97
	v_mul_f32_e32 v162, 0xbfb8aa3b, v98
	v_mul_f32_e32 v163, 0xbfb8aa3b, v99
	v_exp_f32_e32 v108, v108
	v_exp_f32_e32 v109, v109
	v_exp_f32_e32 v110, v110
	v_exp_f32_e32 v111, v111
	v_exp_f32_e32 v104, v104
	v_exp_f32_e32 v105, v105
	v_exp_f32_e32 v106, v106
	v_exp_f32_e32 v107, v107
	v_exp_f32_e32 v100, v100
	v_exp_f32_e32 v101, v101
	v_exp_f32_e32 v102, v102
	v_exp_f32_e32 v103, v103
	v_exp_f32_e32 v160, v160
	v_exp_f32_e32 v161, v161
	v_exp_f32_e32 v162, v162
	v_exp_f32_e32 v163, v163
	v_min_f32_e32 v108, 0x7149f2ca, v108
	v_min_f32_e32 v109, 0x7149f2ca, v109
	v_min_f32_e32 v110, 0x7149f2ca, v110
	v_min_f32_e32 v111, 0x7149f2ca, v111
	v_min_f32_e32 v104, 0x7149f2ca, v104
	v_min_f32_e32 v105, 0x7149f2ca, v105
	v_min_f32_e32 v106, 0x7149f2ca, v106
	v_min_f32_e32 v107, 0x7149f2ca, v107
	v_min_f32_e32 v100, 0x7149f2ca, v100
	v_min_f32_e32 v101, 0x7149f2ca, v101
;     __device__ __forceinline__ void operator()(f32x4 (&acc)[2][2][4][2], const Unit& u, int wr, int wc, int fr, int fq) const {
;     ...
;             for (int ai = 0; ai < 2; ++ai)
; #pragma unroll
;                 for (int m = 0; m < 4; ++m) {
;                     bf16_t* rowp = O + (size_t)(row0q + ai * HALF + m * 16) * LDP + ch;
;                     float r0v[4], r1v[4], g2v[4], szv[4];
; #pragma unroll
;                     for (int j = 0; j < 4; ++j) {
;                         const float ea = fminf(__builtin_amdgcn_exp2f(-1.4426950409f * acc[ai][0][m][0][j]), 1e30f);
;                         const float eb = fminf(__builtin_amdgcn_exp2f(-1.4426950409f * acc[ai][0][m][1][j]), 1e30f);
;                         const float ec = fminf(__builtin_amdgcn_exp2f(-1.4426950409f * acc[ai][1][m][0][j]), 1e30f);
;                         const float xz = acc[ai][1][m][1][j];
;                         const float ia = __builtin_amdgcn_rcpf(1.0f + ea), ib = __builtin_amdgcn_rcpf(1.0f + eb), ic = __builtin_amdgcn_rcpf(1.0f + ec);
;                         r0v[j] = (1.0f + eb) * ia; r1v[j] = (1.0f + ec) * ib; g2v[j] = ic; szv[j] = xz * sigmoid_f(xz);
;                     }
;                     u32x2 wr0, wr1, wg2, wsz;
;                     wr0.x = cvt_pk_bf16(r0v[0], r0v[1]); wr0.y = cvt_pk_bf16(r0v[2], r0v[3]);
;                     wr1.x = cvt_pk_bf16(r1v[0], r1v[1]); wr1.y = cvt_pk_bf16(r1v[2], r1v[3]);
;                     wg2.x = cvt_pk_bf16(g2v[0], g2v[1]); wg2.y = cvt_pk_bf16(g2v[2], g2v[3]);
;                     wsz.x = cvt_pk_bf16(szv[0], szv[1]); wsz.y = cvt_pk_bf16(szv[2], szv[3]);
;                     const bool odd = (fq & 1) != 0;
;                     const u32x2 s0 = odd ? wr0 : wg2, s1 = odd ? wr1 : wsz;
;                     u32x2 q0, q1;
;                     q0.x = (unsigned)__shfl_xor((int)s0.x, 16); q0.y = (unsigned)__shfl_xor((int)s0.y, 16);
;                     q1.x = (unsigned)__shfl_xor((int)s1.x, 16); q1.y = (unsigned)__shfl_xor((int)s1.y, 16);
;                     u32x4 o0, o1;
;                     if (!odd) { o0 = (u32x4){wr0.x, wr0.y, q0.x, q0.y}; o1 = (u32x4){wr1.x, wr1.y, q1.x, q1.y}; }
;                     else      { o0 = (u32x4){q0.x, q0.y, wg2.x, wg2.y}; o1 = (u32x4){q1.x, q1.y, wsz.x, wsz.y}; }
;                     bf16_t* rp8 = rowp - (odd ? 4 : 0);
;                     *(u32x4*)(rp8 + (odd ? S_G2 : S_G0)) = o0;
	v_min_f32_e32 v102, 0x7149f2ca, v102
	v_min_f32_e32 v103, 0x7149f2ca, v103
	v_add_f32_e32 v108, 1.0, v108
	v_add_f32_e32 v109, 1.0, v109
	v_add_f32_e32 v110, 1.0, v110
	v_add_f32_e32 v111, 1.0, v111
	v_add_f32_e32 v104, 1.0, v104
	v_add_f32_e32 v105, 1.0, v105
	v_add_f32_e32 v106, 1.0, v106
	v_add_f32_e32 v107, 1.0, v107
	v_add_f32_e32 v100, 1.0, v100
	v_add_f32_e32 v101, 1.0, v101
	v_add_f32_e32 v102, 1.0, v102
	v_add_f32_e32 v103, 1.0, v103
	v_add_f32_e32 v160, 1.0, v160
	v_add_f32_e32 v161, 1.0, v161
	v_add_f32_e32 v162, 1.0, v162
	v_add_f32_e32 v163, 1.0, v163
	v_rcp_f32_e32 v152, v108
	v_rcp_f32_e32 v153, v109
	v_rcp_f32_e32 v154, v110
	v_rcp_f32_e32 v155, v111
	v_rcp_f32_e32 v156, v104
	v_rcp_f32_e32 v157, v105
	v_rcp_f32_e32 v158, v106
	v_rcp_f32_e32 v159, v107
	v_rcp_f32_e32 v160, v160
	v_rcp_f32_e32 v161, v161
	v_rcp_f32_e32 v162, v162
	v_rcp_f32_e32 v163, v163
	v_mul_f32_e32 v152, v104, v152
	v_mul_f32_e32 v153, v105, v153
	v_mul_f32_e32 v154, v106, v154
	v_mul_f32_e32 v155, v107, v155
	v_mul_f32_e32 v156, v100, v156
	v_mul_f32_e32 v157, v101, v157
	v_mul_f32_e32 v158, v102, v158
	v_mul_f32_e32 v159, v103, v159
	v_rcp_f32_e32 v100, v100
	v_rcp_f32_e32 v101, v101
	v_rcp_f32_e32 v102, v102
	v_rcp_f32_e32 v103, v103
	v_mul_f32_e32 v160, v96, v160
	v_mul_f32_e32 v161, v97, v161
	v_mul_f32_e32 v162, v98, v162
	v_mul_f32_e32 v163, v99, v163
	v_cvt_pk_bf16_f32 v176, v152, v153
	v_cvt_pk_bf16_f32 v177, v154, v155
	v_cvt_pk_bf16_f32 v180, v156, v157
	v_cvt_pk_bf16_f32 v181, v158, v159
	v_cvt_pk_bf16_f32 v182, v160, v161
	v_cvt_pk_bf16_f32 v183, v162, v163
	v_cvt_pk_bf16_f32 v178, v100, v101
	v_cvt_pk_bf16_f32 v179, v102, v103
	s_nop 1
	v_permlane16_swap_b32_e32 v180, v182
	v_permlane16_swap_b32_e32 v181, v183
	v_permlane16_swap_b32_e32 v176, v178
	v_permlane16_swap_b32_e32 v177, v179
	global_store_dwordx4 v151, v[180:183], s[24:25]
	global_store_dwordx4 v150, v[176:179], s[24:25]
	s_add_u32 s24, s24, 0x8000
	s_addc_u32 s25, s25, 0
	v_mul_f32_e32 v92, 0xbfb8aa3b, v92
	v_mul_f32_e32 v93, 0xbfb8aa3b, v93
	v_mul_f32_e32 v94, 0xbfb8aa3b, v94
	v_mul_f32_e32 v95, 0xbfb8aa3b, v95
	v_mul_f32_e32 v88, 0xbfb8aa3b, v88
	v_mul_f32_e32 v89, 0xbfb8aa3b, v89
	v_mul_f32_e32 v90, 0xbfb8aa3b, v90
	v_mul_f32_e32 v91, 0xbfb8aa3b, v91
	v_mul_f32_e32 v84, 0xbfb8aa3b, v84
	v_mul_f32_e32 v85, 0xbfb8aa3b, v85
	v_mul_f32_e32 v86, 0xbfb8aa3b, v86
	v_mul_f32_e32 v87, 0xbfb8aa3b, v87
	v_mul_f32_e32 v160, 0xbfb8aa3b, v80
	v_mul_f32_e32 v161, 0xbfb8aa3b, v81
	v_mul_f32_e32 v162, 0xbfb8aa3b, v82
	v_mul_f32_e32 v163, 0xbfb8aa3b, v83
	v_exp_f32_e32 v92, v92
	v_exp_f32_e32 v93, v93
	v_exp_f32_e32 v94, v94
	v_exp_f32_e32 v95, v95
	v_exp_f32_e32 v88, v88
	v_exp_f32_e32 v89, v89
	v_exp_f32_e32 v90, v90
	v_exp_f32_e32 v91, v91
	v_exp_f32_e32 v84, v84
	v_exp_f32_e32 v85, v85
	v_exp_f32_e32 v86, v86
	v_exp_f32_e32 v87, v87
	v_exp_f32_e32 v160, v160
	v_exp_f32_e32 v161, v161
	v_exp_f32_e32 v162, v162
	v_exp_f32_e32 v163, v163
	v_min_f32_e32 v92, 0x7149f2ca, v92
	v_min_f32_e32 v93, 0x7149f2ca, v93
	v_min_f32_e32 v94, 0x7149f2ca, v94
	v_min_f32_e32 v95, 0x7149f2ca, v95
	v_min_f32_e32 v88, 0x7149f2ca, v88
	v_min_f32_e32 v89, 0x7149f2ca, v89
	v_min_f32_e32 v90, 0x7149f2ca, v90
	v_min_f32_e32 v91, 0x7149f2ca, v91
	v_min_f32_e32 v84, 0x7149f2ca, v84
	v_min_f32_e32 v85, 0x7149f2ca, v85
	v_min_f32_e32 v86, 0x7149f2ca, v86
	v_min_f32_e32 v87, 0x7149f2ca, v87
	v_add_f32_e32 v92, 1.0, v92
	v_add_f32_e32 v93, 1.0, v93
	v_add_f32_e32 v94, 1.0, v94
	v_add_f32_e32 v95, 1.0, v95
	v_add_f32_e32 v88, 1.0, v88
	v_add_f32_e32 v89, 1.0, v89
	v_add_f32_e32 v90, 1.0, v90
	v_add_f32_e32 v91, 1.0, v91
	v_add_f32_e32 v84, 1.0, v84
	v_add_f32_e32 v85, 1.0, v85
	v_add_f32_e32 v86, 1.0, v86
	v_add_f32_e32 v87, 1.0, v87
	v_add_f32_e32 v160, 1.0, v160
	v_add_f32_e32 v161, 1.0, v161
	v_add_f32_e32 v162, 1.0, v162
	v_add_f32_e32 v163, 1.0, v163
	v_rcp_f32_e32 v152, v92
	v_rcp_f32_e32 v153, v93
	v_rcp_f32_e32 v154, v94
	v_rcp_f32_e32 v155, v95
	v_rcp_f32_e32 v156, v88
	v_rcp_f32_e32 v157, v89
	v_rcp_f32_e32 v158, v90
	v_rcp_f32_e32 v159, v91
	v_rcp_f32_e32 v160, v160
	v_rcp_f32_e32 v161, v161
	v_rcp_f32_e32 v162, v162
	v_rcp_f32_e32 v163, v163
	v_mul_f32_e32 v152, v88, v152
	v_mul_f32_e32 v153, v89, v153
	v_mul_f32_e32 v154, v90, v154
	v_mul_f32_e32 v155, v91, v155
	v_mul_f32_e32 v156, v84, v156
	v_mul_f32_e32 v157, v85, v157
	v_mul_f32_e32 v158, v86, v158
	v_mul_f32_e32 v159, v87, v159
	v_rcp_f32_e32 v84, v84
	v_rcp_f32_e32 v85, v85
	v_rcp_f32_e32 v86, v86
	v_rcp_f32_e32 v87, v87
	v_mul_f32_e32 v160, v80, v160
	v_mul_f32_e32 v161, v81, v161
	v_mul_f32_e32 v162, v82, v162
	v_mul_f32_e32 v163, v83, v163
	v_cvt_pk_bf16_f32 v168, v152, v153
	v_cvt_pk_bf16_f32 v169, v154, v155
	v_cvt_pk_bf16_f32 v172, v156, v157
	v_cvt_pk_bf16_f32 v173, v158, v159
	v_cvt_pk_bf16_f32 v174, v160, v161
	v_cvt_pk_bf16_f32 v175, v162, v163
	v_cvt_pk_bf16_f32 v170, v84, v85
	v_cvt_pk_bf16_f32 v171, v86, v87
	s_nop 1
	v_permlane16_swap_b32_e32 v172, v174
	v_permlane16_swap_b32_e32 v173, v175
	v_permlane16_swap_b32_e32 v168, v170
	v_permlane16_swap_b32_e32 v169, v171
	global_store_dwordx4 v151, v[172:175], s[24:25]
	global_store_dwordx4 v150, v[168:171], s[24:25]
	s_add_u32 s24, s24, 0x8000
	s_addc_u32 s25, s25, 0
	v_mul_f32_e32 v76, 0xbfb8aa3b, v76
	v_mul_f32_e32 v77, 0xbfb8aa3b, v77
	v_mul_f32_e32 v78, 0xbfb8aa3b, v78
	v_mul_f32_e32 v79, 0xbfb8aa3b, v79
	v_mul_f32_e32 v72, 0xbfb8aa3b, v72
	v_mul_f32_e32 v73, 0xbfb8aa3b, v73
	v_mul_f32_e32 v74, 0xbfb8aa3b, v74
	v_mul_f32_e32 v75, 0xbfb8aa3b, v75
	v_mul_f32_e32 v68, 0xbfb8aa3b, v68
	v_mul_f32_e32 v69, 0xbfb8aa3b, v69
	v_mul_f32_e32 v70, 0xbfb8aa3b, v70
	v_mul_f32_e32 v71, 0xbfb8aa3b, v71
;     __device__ __forceinline__ void operator()(f32x4 (&acc)[2][2][4][2], const Unit& u, int wr, int wc, int fr, int fq) const {
;     ...
;             for (int ai = 0; ai < 2; ++ai)
; #pragma unroll
;                 for (int m = 0; m < 4; ++m) {
;                     bf16_t* rowp = O + (size_t)(row0q + ai * HALF + m * 16) * LDP + ch;
;                     float r0v[4], r1v[4], g2v[4], szv[4];
; #pragma unroll
;                     for (int j = 0; j < 4; ++j) {
;                         const float ea = fminf(__builtin_amdgcn_exp2f(-1.4426950409f * acc[ai][0][m][0][j]), 1e30f);
;                         const float eb = fminf(__builtin_amdgcn_exp2f(-1.4426950409f * acc[ai][0][m][1][j]), 1e30f);
;                         const float ec = fminf(__builtin_amdgcn_exp2f(-1.4426950409f * acc[ai][1][m][0][j]), 1e30f);
;                         const float xz = acc[ai][1][m][1][j];
;                         const float ia = __builtin_amdgcn_rcpf(1.0f + ea), ib = __builtin_amdgcn_rcpf(1.0f + eb), ic = __builtin_amdgcn_rcpf(1.0f + ec);
;                         r0v[j] = (1.0f + eb) * ia; r1v[j] = (1.0f + ec) * ib; g2v[j] = ic; szv[j] = xz * sigmoid_f(xz);
;                     }
;                     u32x2 wr0, wr1, wg2, wsz;
;                     wr0.x = cvt_pk_bf16(r0v[0], r0v[1]); wr0.y = cvt_pk_bf16(r0v[2], r0v[3]);
;                     wr1.x = cvt_pk_bf16(r1v[0], r1v[1]); wr1.y = cvt_pk_bf16(r1v[2], r1v[3]);
;                     wg2.x = cvt_pk_bf16(g2v[0], g2v[1]); wg2.y = cvt_pk_bf16(g2v[2], g2v[3]);
;                     wsz.x = cvt_pk_bf16(szv[0], szv[1]); wsz.y = cvt_pk_bf16(szv[2], szv[3]);
;                     const bool odd = (fq & 1) != 0;
;                     const u32x2 s0 = odd ? wr0 : wg2, s1 = odd ? wr1 : wsz;
;                     u32x2 q0, q1;
;                     q0.x = (unsigned)__shfl_xor((int)s0.x, 16); q0.y = (unsigned)__shfl_xor((int)s0.y, 16);
;                     q1.x = (unsigned)__shfl_xor((int)s1.x, 16); q1.y = (unsigned)__shfl_xor((int)s1.y, 16);
;                     u32x4 o0, o1;
;                     if (!odd) { o0 = (u32x4){wr0.x, wr0.y, q0.x, q0.y}; o1 = (u32x4){wr1.x, wr1.y, q1.x, q1.y}; }
;                     else      { o0 = (u32x4){q0.x, q0.y, wg2.x, wg2.y}; o1 = (u32x4){q1.x, q1.y, wsz.x, wsz.y}; }
;                     bf16_t* rp8 = rowp - (odd ? 4 : 0);
;                     *(u32x4*)(rp8 + (odd ? S_G2 : S_G0)) = o0;
	v_mul_f32_e32 v160, 0xbfb8aa3b, v64
	v_mul_f32_e32 v161, 0xbfb8aa3b, v65
	v_mul_f32_e32 v162, 0xbfb8aa3b, v66
	v_mul_f32_e32 v163, 0xbfb8aa3b, v67
	v_exp_f32_e32 v76, v76
	v_exp_f32_e32 v77, v77
	v_exp_f32_e32 v78, v78
	v_exp_f32_e32 v79, v79
	v_exp_f32_e32 v72, v72
	v_exp_f32_e32 v73, v73
	v_exp_f32_e32 v74, v74
	v_exp_f32_e32 v75, v75
	v_exp_f32_e32 v68, v68
	v_exp_f32_e32 v69, v69
	v_exp_f32_e32 v70, v70
	v_exp_f32_e32 v71, v71
	v_exp_f32_e32 v160, v160
	v_exp_f32_e32 v161, v161
	v_exp_f32_e32 v162, v162
	v_exp_f32_e32 v163, v163
	v_min_f32_e32 v76, 0x7149f2ca, v76
	v_min_f32_e32 v77, 0x7149f2ca, v77
	v_min_f32_e32 v78, 0x7149f2ca, v78
	v_min_f32_e32 v79, 0x7149f2ca, v79
	v_min_f32_e32 v72, 0x7149f2ca, v72
	v_min_f32_e32 v73, 0x7149f2ca, v73
	v_min_f32_e32 v74, 0x7149f2ca, v74
	v_min_f32_e32 v75, 0x7149f2ca, v75
	v_min_f32_e32 v68, 0x7149f2ca, v68
	v_min_f32_e32 v69, 0x7149f2ca, v69
	v_min_f32_e32 v70, 0x7149f2ca, v70
	v_min_f32_e32 v71, 0x7149f2ca, v71
	v_add_f32_e32 v76, 1.0, v76
	v_add_f32_e32 v77, 1.0, v77
	v_add_f32_e32 v78, 1.0, v78
	v_add_f32_e32 v79, 1.0, v79
	v_add_f32_e32 v72, 1.0, v72
	v_add_f32_e32 v73, 1.0, v73
	v_add_f32_e32 v74, 1.0, v74
	v_add_f32_e32 v75, 1.0, v75
	v_add_f32_e32 v68, 1.0, v68
	v_add_f32_e32 v69, 1.0, v69
	v_add_f32_e32 v70, 1.0, v70
	v_add_f32_e32 v71, 1.0, v71
	v_add_f32_e32 v160, 1.0, v160
	v_add_f32_e32 v161, 1.0, v161
	v_add_f32_e32 v162, 1.0, v162
	v_add_f32_e32 v163, 1.0, v163
	v_rcp_f32_e32 v152, v76
	v_rcp_f32_e32 v153, v77
	v_rcp_f32_e32 v154, v78
	v_rcp_f32_e32 v155, v79
	v_rcp_f32_e32 v156, v72
	v_rcp_f32_e32 v157, v73
	v_rcp_f32_e32 v158, v74
	v_rcp_f32_e32 v159, v75
	v_rcp_f32_e32 v160, v160
	v_rcp_f32_e32 v161, v161
	v_rcp_f32_e32 v162, v162
	v_rcp_f32_e32 v163, v163
	v_mul_f32_e32 v152, v72, v152
	v_mul_f32_e32 v153, v73, v153
	v_mul_f32_e32 v154, v74, v154
	v_mul_f32_e32 v155, v75, v155
	v_mul_f32_e32 v156, v68, v156
	v_mul_f32_e32 v157, v69, v157
	v_mul_f32_e32 v158, v70, v158
	v_mul_f32_e32 v159, v71, v159
	v_rcp_f32_e32 v68, v68
	v_rcp_f32_e32 v69, v69
	v_rcp_f32_e32 v70, v70
	v_rcp_f32_e32 v71, v71
	v_mul_f32_e32 v160, v64, v160
	v_mul_f32_e32 v161, v65, v161
	v_mul_f32_e32 v162, v66, v162
	v_mul_f32_e32 v163, v67, v163
	v_cvt_pk_bf16_f32 v176, v152, v153
	v_cvt_pk_bf16_f32 v177, v154, v155
	v_cvt_pk_bf16_f32 v180, v156, v157
	v_cvt_pk_bf16_f32 v181, v158, v159
	v_cvt_pk_bf16_f32 v182, v160, v161
	v_cvt_pk_bf16_f32 v183, v162, v163
	v_cvt_pk_bf16_f32 v178, v68, v69
	v_cvt_pk_bf16_f32 v179, v70, v71
	s_nop 1
	v_permlane16_swap_b32_e32 v180, v182
	v_permlane16_swap_b32_e32 v181, v183
	v_permlane16_swap_b32_e32 v176, v178
	v_permlane16_swap_b32_e32 v177, v179
	global_store_dwordx4 v151, v[180:183], s[24:25]
	global_store_dwordx4 v150, v[176:179], s[24:25]
	s_add_u32 s24, s24, 0x28000
	s_addc_u32 s25, s25, 0
	v_mul_f32_e32 v60, 0xbfb8aa3b, v60
	v_mul_f32_e32 v61, 0xbfb8aa3b, v61
	v_mul_f32_e32 v62, 0xbfb8aa3b, v62
	v_mul_f32_e32 v63, 0xbfb8aa3b, v63
	v_mul_f32_e32 v56, 0xbfb8aa3b, v56
	v_mul_f32_e32 v57, 0xbfb8aa3b, v57
	v_mul_f32_e32 v58, 0xbfb8aa3b, v58
	v_mul_f32_e32 v59, 0xbfb8aa3b, v59
	v_mul_f32_e32 v52, 0xbfb8aa3b, v52
	v_mul_f32_e32 v53, 0xbfb8aa3b, v53
	v_mul_f32_e32 v54, 0xbfb8aa3b, v54
	v_mul_f32_e32 v55, 0xbfb8aa3b, v55
	v_mul_f32_e32 v160, 0xbfb8aa3b, v48
	v_mul_f32_e32 v161, 0xbfb8aa3b, v49
	v_mul_f32_e32 v162, 0xbfb8aa3b, v50
	v_mul_f32_e32 v163, 0xbfb8aa3b, v51
	v_exp_f32_e32 v60, v60
	v_exp_f32_e32 v61, v61
	v_exp_f32_e32 v62, v62
	v_exp_f32_e32 v63, v63
	v_exp_f32_e32 v56, v56
	v_exp_f32_e32 v57, v57
	v_exp_f32_e32 v58, v58
	v_exp_f32_e32 v59, v59
	v_exp_f32_e32 v52, v52
	v_exp_f32_e32 v53, v53
	v_exp_f32_e32 v54, v54
	v_exp_f32_e32 v55, v55
	v_exp_f32_e32 v160, v160
	v_exp_f32_e32 v161, v161
	v_exp_f32_e32 v162, v162
	v_exp_f32_e32 v163, v163
	v_min_f32_e32 v60, 0x7149f2ca, v60
	v_min_f32_e32 v61, 0x7149f2ca, v61
	v_min_f32_e32 v62, 0x7149f2ca, v62
	v_min_f32_e32 v63, 0x7149f2ca, v63
	v_min_f32_e32 v56, 0x7149f2ca, v56
	v_min_f32_e32 v57, 0x7149f2ca, v57
	v_min_f32_e32 v58, 0x7149f2ca, v58
	v_min_f32_e32 v59, 0x7149f2ca, v59
	v_min_f32_e32 v52, 0x7149f2ca, v52
	v_min_f32_e32 v53, 0x7149f2ca, v53
	v_min_f32_e32 v54, 0x7149f2ca, v54
	v_min_f32_e32 v55, 0x7149f2ca, v55
	v_add_f32_e32 v60, 1.0, v60
	v_add_f32_e32 v61, 1.0, v61
	v_add_f32_e32 v62, 1.0, v62
	v_add_f32_e32 v63, 1.0, v63
	v_add_f32_e32 v56, 1.0, v56
	v_add_f32_e32 v57, 1.0, v57
	v_add_f32_e32 v58, 1.0, v58
	v_add_f32_e32 v59, 1.0, v59
	v_add_f32_e32 v52, 1.0, v52
	v_add_f32_e32 v53, 1.0, v53
	v_add_f32_e32 v54, 1.0, v54
	v_add_f32_e32 v55, 1.0, v55
	v_add_f32_e32 v160, 1.0, v160
	v_add_f32_e32 v161, 1.0, v161
	v_add_f32_e32 v162, 1.0, v162
	v_add_f32_e32 v163, 1.0, v163
	v_rcp_f32_e32 v152, v60
	v_rcp_f32_e32 v153, v61
	v_rcp_f32_e32 v154, v62
	v_rcp_f32_e32 v155, v63
	v_rcp_f32_e32 v156, v56
	v_rcp_f32_e32 v157, v57
	v_rcp_f32_e32 v158, v58
	v_rcp_f32_e32 v159, v59
	v_rcp_f32_e32 v160, v160
	v_rcp_f32_e32 v161, v161
	v_rcp_f32_e32 v162, v162
	v_rcp_f32_e32 v163, v163
	v_mul_f32_e32 v152, v56, v152
	v_mul_f32_e32 v153, v57, v153
	v_mul_f32_e32 v154, v58, v154
	v_mul_f32_e32 v155, v59, v155
	v_mul_f32_e32 v156, v52, v156
	v_mul_f32_e32 v157, v53, v157
	v_mul_f32_e32 v158, v54, v158
	v_mul_f32_e32 v159, v55, v159
	v_rcp_f32_e32 v52, v52
	v_rcp_f32_e32 v53, v53
	v_rcp_f32_e32 v54, v54
	v_rcp_f32_e32 v55, v55
	v_mul_f32_e32 v160, v48, v160
	v_mul_f32_e32 v161, v49, v161
	v_mul_f32_e32 v162, v50, v162
	v_mul_f32_e32 v163, v51, v163
	v_cvt_pk_bf16_f32 v168, v152, v153
	v_cvt_pk_bf16_f32 v169, v154, v155
	v_cvt_pk_bf16_f32 v172, v156, v157
	v_cvt_pk_bf16_f32 v173, v158, v159
	v_cvt_pk_bf16_f32 v174, v160, v161
;     __device__ __forceinline__ void operator()(f32x4 (&acc)[2][2][4][2], const Unit& u, int wr, int wc, int fr, int fq) const {
;     ...
;             for (int ai = 0; ai < 2; ++ai)
; #pragma unroll
;                 for (int m = 0; m < 4; ++m) {
;                     bf16_t* rowp = O + (size_t)(row0q + ai * HALF + m * 16) * LDP + ch;
;                     float r0v[4], r1v[4], g2v[4], szv[4];
; #pragma unroll
;                     for (int j = 0; j < 4; ++j) {
;                         const float ea = fminf(__builtin_amdgcn_exp2f(-1.4426950409f * acc[ai][0][m][0][j]), 1e30f);
;                         const float eb = fminf(__builtin_amdgcn_exp2f(-1.4426950409f * acc[ai][0][m][1][j]), 1e30f);
;                         const float ec = fminf(__builtin_amdgcn_exp2f(-1.4426950409f * acc[ai][1][m][0][j]), 1e30f);
;                         const float xz = acc[ai][1][m][1][j];
;                         const float ia = __builtin_amdgcn_rcpf(1.0f + ea), ib = __builtin_amdgcn_rcpf(1.0f + eb), ic = __builtin_amdgcn_rcpf(1.0f + ec);
;                         r0v[j] = (1.0f + eb) * ia; r1v[j] = (1.0f + ec) * ib; g2v[j] = ic; szv[j] = xz * sigmoid_f(xz);
;                     }
;                     u32x2 wr0, wr1, wg2, wsz;
;                     wr0.x = cvt_pk_bf16(r0v[0], r0v[1]); wr0.y = cvt_pk_bf16(r0v[2], r0v[3]);
;                     wr1.x = cvt_pk_bf16(r1v[0], r1v[1]); wr1.y = cvt_pk_bf16(r1v[2], r1v[3]);
;                     wg2.x = cvt_pk_bf16(g2v[0], g2v[1]); wg2.y = cvt_pk_bf16(g2v[2], g2v[3]);
;                     wsz.x = cvt_pk_bf16(szv[0], szv[1]); wsz.y = cvt_pk_bf16(szv[2], szv[3]);
;                     const bool odd = (fq & 1) != 0;
;                     const u32x2 s0 = odd ? wr0 : wg2, s1 = odd ? wr1 : wsz;
;                     u32x2 q0, q1;
;                     q0.x = (unsigned)__shfl_xor((int)s0.x, 16); q0.y = (unsigned)__shfl_xor((int)s0.y, 16);
;                     q1.x = (unsigned)__shfl_xor((int)s1.x, 16); q1.y = (unsigned)__shfl_xor((int)s1.y, 16);
;                     u32x4 o0, o1;
;                     if (!odd) { o0 = (u32x4){wr0.x, wr0.y, q0.x, q0.y}; o1 = (u32x4){wr1.x, wr1.y, q1.x, q1.y}; }
;                     else      { o0 = (u32x4){q0.x, q0.y, wg2.x, wg2.y}; o1 = (u32x4){q1.x, q1.y, wsz.x, wsz.y}; }
;                     bf16_t* rp8 = rowp - (odd ? 4 : 0);
;                     *(u32x4*)(rp8 + (odd ? S_G2 : S_G0)) = o0;
	v_cvt_pk_bf16_f32 v175, v162, v163
	v_cvt_pk_bf16_f32 v170, v52, v53
	v_cvt_pk_bf16_f32 v171, v54, v55
	s_nop 1
	v_permlane16_swap_b32_e32 v172, v174
	v_permlane16_swap_b32_e32 v173, v175
	v_permlane16_swap_b32_e32 v168, v170
	v_permlane16_swap_b32_e32 v169, v171
	global_store_dwordx4 v151, v[172:175], s[24:25]
	global_store_dwordx4 v150, v[168:171], s[24:25]
	s_add_u32 s24, s24, 0x8000
	s_addc_u32 s25, s25, 0
	v_mul_f32_e32 v44, 0xbfb8aa3b, v44
	v_mul_f32_e32 v45, 0xbfb8aa3b, v45
	v_mul_f32_e32 v46, 0xbfb8aa3b, v46
	v_mul_f32_e32 v47, 0xbfb8aa3b, v47
	v_mul_f32_e32 v40, 0xbfb8aa3b, v40
	v_mul_f32_e32 v41, 0xbfb8aa3b, v41
	v_mul_f32_e32 v42, 0xbfb8aa3b, v42
	v_mul_f32_e32 v43, 0xbfb8aa3b, v43
	v_mul_f32_e32 v36, 0xbfb8aa3b, v36
	v_mul_f32_e32 v37, 0xbfb8aa3b, v37
	v_mul_f32_e32 v38, 0xbfb8aa3b, v38
	v_mul_f32_e32 v39, 0xbfb8aa3b, v39
	v_mul_f32_e32 v160, 0xbfb8aa3b, v32
	v_mul_f32_e32 v161, 0xbfb8aa3b, v33
	v_mul_f32_e32 v162, 0xbfb8aa3b, v34
	v_mul_f32_e32 v163, 0xbfb8aa3b, v35
	v_exp_f32_e32 v44, v44
	v_exp_f32_e32 v45, v45
	v_exp_f32_e32 v46, v46
	v_exp_f32_e32 v47, v47
	v_exp_f32_e32 v40, v40
	v_exp_f32_e32 v41, v41
	v_exp_f32_e32 v42, v42
	v_exp_f32_e32 v43, v43
	v_exp_f32_e32 v36, v36
	v_exp_f32_e32 v37, v37
	v_exp_f32_e32 v38, v38
	v_exp_f32_e32 v39, v39
	v_exp_f32_e32 v160, v160
	v_exp_f32_e32 v161, v161
	v_exp_f32_e32 v162, v162
	v_exp_f32_e32 v163, v163
	v_min_f32_e32 v44, 0x7149f2ca, v44
	v_min_f32_e32 v45, 0x7149f2ca, v45
	v_min_f32_e32 v46, 0x7149f2ca, v46
	v_min_f32_e32 v47, 0x7149f2ca, v47
	v_min_f32_e32 v40, 0x7149f2ca, v40
	v_min_f32_e32 v41, 0x7149f2ca, v41
	v_min_f32_e32 v42, 0x7149f2ca, v42
	v_min_f32_e32 v43, 0x7149f2ca, v43
	v_min_f32_e32 v36, 0x7149f2ca, v36
	v_min_f32_e32 v37, 0x7149f2ca, v37
	v_min_f32_e32 v38, 0x7149f2ca, v38
	v_min_f32_e32 v39, 0x7149f2ca, v39
	v_add_f32_e32 v44, 1.0, v44
	v_add_f32_e32 v45, 1.0, v45
	v_add_f32_e32 v46, 1.0, v46
	v_add_f32_e32 v47, 1.0, v47
	v_add_f32_e32 v40, 1.0, v40
	v_add_f32_e32 v41, 1.0, v41
	v_add_f32_e32 v42, 1.0, v42
	v_add_f32_e32 v43, 1.0, v43
	v_add_f32_e32 v36, 1.0, v36
	v_add_f32_e32 v37, 1.0, v37
	v_add_f32_e32 v38, 1.0, v38
	v_add_f32_e32 v39, 1.0, v39
	v_add_f32_e32 v160, 1.0, v160
	v_add_f32_e32 v161, 1.0, v161
	v_add_f32_e32 v162, 1.0, v162
	v_add_f32_e32 v163, 1.0, v163
	v_rcp_f32_e32 v152, v44
	v_rcp_f32_e32 v153, v45
	v_rcp_f32_e32 v154, v46
	v_rcp_f32_e32 v155, v47
	v_rcp_f32_e32 v156, v40
	v_rcp_f32_e32 v157, v41
	v_rcp_f32_e32 v158, v42
	v_rcp_f32_e32 v159, v43
	v_rcp_f32_e32 v160, v160
	v_rcp_f32_e32 v161, v161
	v_rcp_f32_e32 v162, v162
	v_rcp_f32_e32 v163, v163
	v_mul_f32_e32 v152, v40, v152
	v_mul_f32_e32 v153, v41, v153
	v_mul_f32_e32 v154, v42, v154
	v_mul_f32_e32 v155, v43, v155
	v_mul_f32_e32 v156, v36, v156
	v_mul_f32_e32 v157, v37, v157
	v_mul_f32_e32 v158, v38, v158
	v_mul_f32_e32 v159, v39, v159
	v_rcp_f32_e32 v36, v36
	v_rcp_f32_e32 v37, v37
	v_rcp_f32_e32 v38, v38
	v_rcp_f32_e32 v39, v39
	v_mul_f32_e32 v160, v32, v160
	v_mul_f32_e32 v161, v33, v161
	v_mul_f32_e32 v162, v34, v162
	v_mul_f32_e32 v163, v35, v163
	v_cvt_pk_bf16_f32 v176, v152, v153
	v_cvt_pk_bf16_f32 v177, v154, v155
	v_cvt_pk_bf16_f32 v180, v156, v157
	v_cvt_pk_bf16_f32 v181, v158, v159
	v_cvt_pk_bf16_f32 v182, v160, v161
	v_cvt_pk_bf16_f32 v183, v162, v163
	v_cvt_pk_bf16_f32 v178, v36, v37
	v_cvt_pk_bf16_f32 v179, v38, v39
	s_nop 1
	v_permlane16_swap_b32_e32 v180, v182
	v_permlane16_swap_b32_e32 v181, v183
	v_permlane16_swap_b32_e32 v176, v178
	v_permlane16_swap_b32_e32 v177, v179
	global_store_dwordx4 v151, v[180:183], s[24:25]
	global_store_dwordx4 v150, v[176:179], s[24:25]
	s_add_u32 s24, s24, 0x8000
	s_addc_u32 s25, s25, 0
	v_mul_f32_e32 v28, 0xbfb8aa3b, v28
	v_mul_f32_e32 v29, 0xbfb8aa3b, v29
	v_mul_f32_e32 v30, 0xbfb8aa3b, v30
	v_mul_f32_e32 v31, 0xbfb8aa3b, v31
	v_mul_f32_e32 v24, 0xbfb8aa3b, v24
	v_mul_f32_e32 v25, 0xbfb8aa3b, v25
	v_mul_f32_e32 v26, 0xbfb8aa3b, v26
	v_mul_f32_e32 v27, 0xbfb8aa3b, v27
	v_mul_f32_e32 v20, 0xbfb8aa3b, v20
	v_mul_f32_e32 v21, 0xbfb8aa3b, v21
	v_mul_f32_e32 v22, 0xbfb8aa3b, v22
	v_mul_f32_e32 v23, 0xbfb8aa3b, v23
	v_mul_f32_e32 v160, 0xbfb8aa3b, v16
	v_mul_f32_e32 v161, 0xbfb8aa3b, v17
	v_mul_f32_e32 v162, 0xbfb8aa3b, v18
	v_mul_f32_e32 v163, 0xbfb8aa3b, v19
	v_exp_f32_e32 v28, v28
	v_exp_f32_e32 v29, v29
	v_exp_f32_e32 v30, v30
	v_exp_f32_e32 v31, v31
	v_exp_f32_e32 v24, v24
	v_exp_f32_e32 v25, v25
	v_exp_f32_e32 v26, v26
	v_exp_f32_e32 v27, v27
	v_exp_f32_e32 v20, v20
	v_exp_f32_e32 v21, v21
	v_exp_f32_e32 v22, v22
	v_exp_f32_e32 v23, v23
	v_exp_f32_e32 v160, v160
	v_exp_f32_e32 v161, v161
	v_exp_f32_e32 v162, v162
	v_exp_f32_e32 v163, v163
	v_min_f32_e32 v28, 0x7149f2ca, v28
	v_min_f32_e32 v29, 0x7149f2ca, v29
	v_min_f32_e32 v30, 0x7149f2ca, v30
	v_min_f32_e32 v31, 0x7149f2ca, v31
	v_min_f32_e32 v24, 0x7149f2ca, v24
	v_min_f32_e32 v25, 0x7149f2ca, v25
	v_min_f32_e32 v26, 0x7149f2ca, v26
	v_min_f32_e32 v27, 0x7149f2ca, v27
	v_min_f32_e32 v20, 0x7149f2ca, v20
	v_min_f32_e32 v21, 0x7149f2ca, v21
	v_min_f32_e32 v22, 0x7149f2ca, v22
;     __device__ __forceinline__ void operator()(f32x4 (&acc)[2][2][4][2], const Unit& u, int wr, int wc, int fr, int fq) const {
;     ...
;             for (int ai = 0; ai < 2; ++ai)
; #pragma unroll
;                 for (int m = 0; m < 4; ++m) {
;                     bf16_t* rowp = O + (size_t)(row0q + ai * HALF + m * 16) * LDP + ch;
;                     float r0v[4], r1v[4], g2v[4], szv[4];
; #pragma unroll
;                     for (int j = 0; j < 4; ++j) {
;                         const float ea = fminf(__builtin_amdgcn_exp2f(-1.4426950409f * acc[ai][0][m][0][j]), 1e30f);
;                         const float eb = fminf(__builtin_amdgcn_exp2f(-1.4426950409f * acc[ai][0][m][1][j]), 1e30f);
;                         const float ec = fminf(__builtin_amdgcn_exp2f(-1.4426950409f * acc[ai][1][m][0][j]), 1e30f);
;                         const float xz = acc[ai][1][m][1][j];
;                         const float ia = __builtin_amdgcn_rcpf(1.0f + ea), ib = __builtin_amdgcn_rcpf(1.0f + eb), ic = __builtin_amdgcn_rcpf(1.0f + ec);
;                         r0v[j] = (1.0f + eb) * ia; r1v[j] = (1.0f + ec) * ib; g2v[j] = ic; szv[j] = xz * sigmoid_f(xz);
;                     }
;                     u32x2 wr0, wr1, wg2, wsz;
;                     wr0.x = cvt_pk_bf16(r0v[0], r0v[1]); wr0.y = cvt_pk_bf16(r0v[2], r0v[3]);
;                     wr1.x = cvt_pk_bf16(r1v[0], r1v[1]); wr1.y = cvt_pk_bf16(r1v[2], r1v[3]);
;                     wg2.x = cvt_pk_bf16(g2v[0], g2v[1]); wg2.y = cvt_pk_bf16(g2v[2], g2v[3]);
;                     wsz.x = cvt_pk_bf16(szv[0], szv[1]); wsz.y = cvt_pk_bf16(szv[2], szv[3]);
;                     const bool odd = (fq & 1) != 0;
;                     const u32x2 s0 = odd ? wr0 : wg2, s1 = odd ? wr1 : wsz;
;                     u32x2 q0, q1;
;                     q0.x = (unsigned)__shfl_xor((int)s0.x, 16); q0.y = (unsigned)__shfl_xor((int)s0.y, 16);
;                     q1.x = (unsigned)__shfl_xor((int)s1.x, 16); q1.y = (unsigned)__shfl_xor((int)s1.y, 16);
;                     u32x4 o0, o1;
;                     if (!odd) { o0 = (u32x4){wr0.x, wr0.y, q0.x, q0.y}; o1 = (u32x4){wr1.x, wr1.y, q1.x, q1.y}; }
;                     else      { o0 = (u32x4){q0.x, q0.y, wg2.x, wg2.y}; o1 = (u32x4){q1.x, q1.y, wsz.x, wsz.y}; }
;                     bf16_t* rp8 = rowp - (odd ? 4 : 0);
;                     *(u32x4*)(rp8 + (odd ? S_G2 : S_G0)) = o0;
	v_min_f32_e32 v23, 0x7149f2ca, v23
	v_add_f32_e32 v28, 1.0, v28
	v_add_f32_e32 v29, 1.0, v29
	v_add_f32_e32 v30, 1.0, v30
	v_add_f32_e32 v31, 1.0, v31
	v_add_f32_e32 v24, 1.0, v24
	v_add_f32_e32 v25, 1.0, v25
	v_add_f32_e32 v26, 1.0, v26
	v_add_f32_e32 v27, 1.0, v27
	v_add_f32_e32 v20, 1.0, v20
	v_add_f32_e32 v21, 1.0, v21
	v_add_f32_e32 v22, 1.0, v22
	v_add_f32_e32 v23, 1.0, v23
	v_add_f32_e32 v160, 1.0, v160
	v_add_f32_e32 v161, 1.0, v161
	v_add_f32_e32 v162, 1.0, v162
	v_add_f32_e32 v163, 1.0, v163
	v_rcp_f32_e32 v152, v28
	v_rcp_f32_e32 v153, v29
	v_rcp_f32_e32 v154, v30
	v_rcp_f32_e32 v155, v31
	v_rcp_f32_e32 v156, v24
	v_rcp_f32_e32 v157, v25
	v_rcp_f32_e32 v158, v26
	v_rcp_f32_e32 v159, v27
	v_rcp_f32_e32 v160, v160
	v_rcp_f32_e32 v161, v161
	v_rcp_f32_e32 v162, v162
	v_rcp_f32_e32 v163, v163
	v_mul_f32_e32 v152, v24, v152
	v_mul_f32_e32 v153, v25, v153
	v_mul_f32_e32 v154, v26, v154
	v_mul_f32_e32 v155, v27, v155
	v_mul_f32_e32 v156, v20, v156
	v_mul_f32_e32 v157, v21, v157
	v_mul_f32_e32 v158, v22, v158
	v_mul_f32_e32 v159, v23, v159
	v_rcp_f32_e32 v20, v20
	v_rcp_f32_e32 v21, v21
	v_rcp_f32_e32 v22, v22
	v_rcp_f32_e32 v23, v23
	v_mul_f32_e32 v160, v16, v160
	v_mul_f32_e32 v161, v17, v161
	v_mul_f32_e32 v162, v18, v162
	v_mul_f32_e32 v163, v19, v163
	v_cvt_pk_bf16_f32 v168, v152, v153
	v_cvt_pk_bf16_f32 v169, v154, v155
	v_cvt_pk_bf16_f32 v172, v156, v157
	v_cvt_pk_bf16_f32 v173, v158, v159
	v_cvt_pk_bf16_f32 v174, v160, v161
	v_cvt_pk_bf16_f32 v175, v162, v163
	v_cvt_pk_bf16_f32 v170, v20, v21
	v_cvt_pk_bf16_f32 v171, v22, v23
	s_nop 1
	v_permlane16_swap_b32_e32 v172, v174
	v_permlane16_swap_b32_e32 v173, v175
	v_permlane16_swap_b32_e32 v168, v170
	v_permlane16_swap_b32_e32 v169, v171
	global_store_dwordx4 v151, v[172:175], s[24:25]
	global_store_dwordx4 v150, v[168:171], s[24:25]
	s_add_u32 s24, s24, 0x8000
	s_addc_u32 s25, s25, 0
	v_mul_f32_e32 v12, 0xbfb8aa3b, v12
	v_mul_f32_e32 v13, 0xbfb8aa3b, v13
	v_mul_f32_e32 v14, 0xbfb8aa3b, v14
	v_mul_f32_e32 v15, 0xbfb8aa3b, v15
	v_mul_f32_e32 v8, 0xbfb8aa3b, v8
	v_mul_f32_e32 v9, 0xbfb8aa3b, v9
	v_mul_f32_e32 v10, 0xbfb8aa3b, v10
	v_mul_f32_e32 v11, 0xbfb8aa3b, v11
	v_mul_f32_e32 v4, 0xbfb8aa3b, v4
	v_mul_f32_e32 v5, 0xbfb8aa3b, v5
	v_mul_f32_e32 v6, 0xbfb8aa3b, v6
	v_mul_f32_e32 v7, 0xbfb8aa3b, v7
	v_mul_f32_e32 v160, 0xbfb8aa3b, v0
	v_mul_f32_e32 v161, 0xbfb8aa3b, v1
	v_mul_f32_e32 v162, 0xbfb8aa3b, v2
	v_mul_f32_e32 v163, 0xbfb8aa3b, v3
	v_exp_f32_e32 v12, v12
	v_exp_f32_e32 v13, v13
	v_exp_f32_e32 v14, v14
	v_exp_f32_e32 v15, v15
	v_exp_f32_e32 v8, v8
	v_exp_f32_e32 v9, v9
	v_exp_f32_e32 v10, v10
	v_exp_f32_e32 v11, v11
	v_exp_f32_e32 v4, v4
	v_exp_f32_e32 v5, v5
	v_exp_f32_e32 v6, v6
	v_exp_f32_e32 v7, v7
	v_exp_f32_e32 v160, v160
	v_exp_f32_e32 v161, v161
	v_exp_f32_e32 v162, v162
	v_exp_f32_e32 v163, v163
	v_min_f32_e32 v12, 0x7149f2ca, v12
	v_min_f32_e32 v13, 0x7149f2ca, v13
	v_min_f32_e32 v14, 0x7149f2ca, v14
	v_min_f32_e32 v15, 0x7149f2ca, v15
	v_min_f32_e32 v8, 0x7149f2ca, v8
	v_min_f32_e32 v9, 0x7149f2ca, v9
	v_min_f32_e32 v10, 0x7149f2ca, v10
	v_min_f32_e32 v11, 0x7149f2ca, v11
	v_min_f32_e32 v4, 0x7149f2ca, v4
	v_min_f32_e32 v5, 0x7149f2ca, v5
	v_min_f32_e32 v6, 0x7149f2ca, v6
	v_min_f32_e32 v7, 0x7149f2ca, v7
	v_add_f32_e32 v12, 1.0, v12
	v_add_f32_e32 v13, 1.0, v13
	v_add_f32_e32 v14, 1.0, v14
	v_add_f32_e32 v15, 1.0, v15
	v_add_f32_e32 v8, 1.0, v8
	v_add_f32_e32 v9, 1.0, v9
	v_add_f32_e32 v10, 1.0, v10
	v_add_f32_e32 v11, 1.0, v11
	v_add_f32_e32 v4, 1.0, v4
	v_add_f32_e32 v5, 1.0, v5
	v_add_f32_e32 v6, 1.0, v6
	v_add_f32_e32 v7, 1.0, v7
	v_add_f32_e32 v160, 1.0, v160
	v_add_f32_e32 v161, 1.0, v161
	v_add_f32_e32 v162, 1.0, v162
	v_add_f32_e32 v163, 1.0, v163
	v_rcp_f32_e32 v152, v12
	v_rcp_f32_e32 v153, v13
	v_rcp_f32_e32 v154, v14
	v_rcp_f32_e32 v155, v15
	v_rcp_f32_e32 v156, v8
	v_rcp_f32_e32 v157, v9
	v_rcp_f32_e32 v158, v10
	v_rcp_f32_e32 v159, v11
	v_rcp_f32_e32 v160, v160
	v_rcp_f32_e32 v161, v161
	v_rcp_f32_e32 v162, v162
	v_rcp_f32_e32 v163, v163
	v_mul_f32_e32 v152, v8, v152
	v_mul_f32_e32 v153, v9, v153
	v_mul_f32_e32 v154, v10, v154
	v_mul_f32_e32 v155, v11, v155
	v_mul_f32_e32 v156, v4, v156
	v_mul_f32_e32 v157, v5, v157
	v_mul_f32_e32 v158, v6, v158
	v_mul_f32_e32 v159, v7, v159
	v_rcp_f32_e32 v4, v4
	v_rcp_f32_e32 v5, v5
	v_rcp_f32_e32 v6, v6
	v_rcp_f32_e32 v7, v7
	v_mul_f32_e32 v160, v0, v160
	v_mul_f32_e32 v161, v1, v161
	v_mul_f32_e32 v162, v2, v162
	v_mul_f32_e32 v163, v3, v163
	v_cvt_pk_bf16_f32 v176, v152, v153
	v_cvt_pk_bf16_f32 v177, v154, v155
	v_cvt_pk_bf16_f32 v180, v156, v157
	v_cvt_pk_bf16_f32 v181, v158, v159
	v_cvt_pk_bf16_f32 v182, v160, v161
	v_cvt_pk_bf16_f32 v183, v162, v163
	v_cvt_pk_bf16_f32 v178, v4, v5
	v_cvt_pk_bf16_f32 v179, v6, v7
	s_nop 1
	v_permlane16_swap_b32_e32 v180, v182
	v_permlane16_swap_b32_e32 v181, v183
	v_permlane16_swap_b32_e32 v176, v178
	v_permlane16_swap_b32_e32 v177, v179
	global_store_dwordx4 v151, v[180:183], s[24:25]
	global_store_dwordx4 v150, v[176:179], s[24:25]
	s_branch .LBB0_298
.LBB0_491:
	s_mov_b64 s[4:5], 0
	s_branch .LBB0_496
